# P5 GLU GEMM: next chunk's weight loads stay in flight across the second MFMA block (counted waits), first chunk issued before the barrier
# speedup vs baseline: 1.0149x; 1.0014x over previous
.LBB0_456:
	v_or_b32_e32 v0, s12, v136
	v_mad_u32_u24 v0, v0, s17, v138
	ds_read_b128 v[48:51], v0
	v_add_u32_e32 v205, 0x400, v221
	v_add_u32_e32 v231, 0x800, v221
	v_add_u32_e32 v234, 0xc00, v221
	v_add_u32_e32 v235, 0x1000, v221
	s_waitcnt lgkmcnt(0)
	v_mfma_f32_32x32x16_bf16 v[0:15], v[64:67], v[48:51], 0
	v_add_u32_e32 v236, 0x1200, v221
	v_add_u32_e32 v237, 0x1400, v221
	v_add_u32_e32 v238, 0x1600, v221
	v_add_u32_e32 v239, 0x1800, v221
	v_add_u32_e32 v240, 0x1a00, v221
	v_add_u32_e32 v241, 0x1c00, v221
	v_add_u32_e32 v242, 0x1e00, v221
	v_mfma_f32_32x32x16_bf16 v[16:31], v[68:71], v[48:51], 0
	s_nop 3
	v_cvt_pk_bf16_f32 v0, v0, v1
	v_cvt_pk_bf16_f32 v1, v2, v3
	v_cvt_pk_bf16_f32 v2, v4, v5
	v_cvt_pk_bf16_f32 v3, v6, v7
	v_cvt_pk_bf16_f32 v4, v8, v9
	v_cvt_pk_bf16_f32 v5, v10, v11
	v_cvt_pk_bf16_f32 v6, v12, v13
	v_mfma_f32_32x32x16_bf16 v[32:47], v[72:75], v[48:51], 0
	v_cvt_pk_bf16_f32 v7, v14, v15
	v_cvt_pk_bf16_f32 v8, v16, v17
	v_cvt_pk_bf16_f32 v9, v18, v19
	v_cvt_pk_bf16_f32 v10, v20, v21
	v_cvt_pk_bf16_f32 v11, v22, v23
	v_cvt_pk_bf16_f32 v12, v24, v25
	v_cvt_pk_bf16_f32 v13, v26, v27
	v_mfma_f32_32x32x16_bf16 v[48:63], v[76:79], v[48:51], 0
	v_cvt_pk_bf16_f32 v14, v28, v29
	v_cvt_pk_bf16_f32 v15, v30, v31
	s_nop 1
	v_cvt_pk_bf16_f32 v16, v32, v33
	v_cvt_pk_bf16_f32 v17, v34, v35
	v_cvt_pk_bf16_f32 v18, v36, v37
	v_cvt_pk_bf16_f32 v19, v38, v39
	v_cvt_pk_bf16_f32 v20, v40, v41
	v_cvt_pk_bf16_f32 v21, v42, v43
	v_cvt_pk_bf16_f32 v22, v44, v45
	v_cvt_pk_bf16_f32 v23, v46, v47
	v_cvt_pk_bf16_f32 v24, v48, v49
	v_cvt_pk_bf16_f32 v25, v50, v51
	v_cvt_pk_bf16_f32 v26, v52, v53
	v_cvt_pk_bf16_f32 v27, v54, v55
	v_cvt_pk_bf16_f32 v28, v56, v57
	v_cvt_pk_bf16_f32 v29, v58, v59
	v_cvt_pk_bf16_f32 v30, v60, v61
	v_cvt_pk_bf16_f32 v31, v62, v63
	ds_write2_b64 v220, v[0:1], v[2:3] offset1:2
	ds_write2_b64 v220, v[4:5], v[6:7] offset0:4 offset1:6
	ds_write2_b64 v220, v[8:9], v[10:11] offset0:8 offset1:10
	ds_write2_b64 v220, v[12:13], v[14:15] offset0:12 offset1:14
	ds_write2_b64 v220, v[16:17], v[18:19] offset0:16 offset1:18
	ds_write2_b64 v220, v[20:21], v[22:23] offset0:20 offset1:22
	ds_write2_b64 v220, v[24:25], v[26:27] offset0:24 offset1:26
	ds_write2_b64 v220, v[28:29], v[30:31] offset0:28 offset1:30
	s_waitcnt lgkmcnt(0)
	ds_read2_b32 v[0:1], v221 offset1:68
	ds_read2_b32 v[2:3], v221 offset0:136 offset1:204
	ds_read2_b32 v[4:5], v205 offset0:16 offset1:84
	ds_read2_b32 v[6:7], v205 offset0:152 offset1:220
	ds_read2_b32 v[8:9], v231 offset0:32 offset1:100
	ds_read2_b32 v[10:11], v231 offset0:168 offset1:236
	ds_read2_b32 v[12:13], v234 offset0:48 offset1:116
	ds_read2_b32 v[14:15], v234 offset0:184 offset1:252
	ds_read2_b32 v[16:17], v235 offset0:64 offset1:132
	ds_read2_b32 v[18:19], v236 offset0:72 offset1:140
	ds_read2_b32 v[20:21], v237 offset0:80 offset1:148
	ds_read2_b32 v[22:23], v238 offset0:88 offset1:156
	ds_read2_b32 v[24:25], v239 offset0:96 offset1:164
	ds_read2_b32 v[26:27], v240 offset0:104 offset1:172
	ds_read2_b32 v[28:29], v241 offset0:112 offset1:180
	ds_read2_b32 v[30:31], v242 offset0:120 offset1:188
	s_waitcnt lgkmcnt(14)
	v_lshlrev_b32_e32 v32, 16, v0
	v_and_b32_e32 v33, 0xffff0000, v0
	s_waitcnt lgkmcnt(5)
	v_lshlrev_b32_e32 v52, 16, v20
	v_and_b32_e32 v53, 0xffff0000, v20
	v_lshlrev_b32_e32 v55, 16, v21
	v_and_b32_e32 v54, 0xffff0000, v21
	s_waitcnt lgkmcnt(4)
	v_lshlrev_b32_e32 v20, 16, v22
	v_and_b32_e32 v21, 0xffff0000, v22
	v_lshlrev_b32_e32 v57, 16, v23
	v_and_b32_e32 v56, 0xffff0000, v23
	s_waitcnt lgkmcnt(3)
	v_lshlrev_b32_e32 v23, 16, v24
	v_and_b32_e32 v22, 0xffff0000, v24
	v_lshlrev_b32_e32 v59, 16, v25
	v_and_b32_e32 v58, 0xffff0000, v25
	s_waitcnt lgkmcnt(2)
	v_lshlrev_b32_e32 v25, 16, v26
	v_and_b32_e32 v24, 0xffff0000, v26
	v_lshlrev_b32_e32 v61, 16, v27
	v_and_b32_e32 v60, 0xffff0000, v27
	s_waitcnt lgkmcnt(1)
	v_lshlrev_b32_e32 v27, 16, v28
	v_and_b32_e32 v26, 0xffff0000, v28
	v_lshlrev_b32_e32 v63, 16, v29
	v_and_b32_e32 v62, 0xffff0000, v29
	s_waitcnt lgkmcnt(0)
	v_lshlrev_b32_e32 v29, 16, v30
	v_and_b32_e32 v28, 0xffff0000, v30
	v_lshlrev_b32_e32 v233, 16, v31
	v_and_b32_e32 v232, 0xffff0000, v31
	v_pk_fma_f32 v[30:31], v[206:207], v[216:217], v[32:33]
	v_lshlrev_b32_e32 v0, 16, v1
	v_and_b32_e32 v1, 0xffff0000, v1
	v_pk_fma_f32 v[30:31], v[214:215], v[216:217], v[30:31] op_sel:[0,1,0] op_sel_hi:[1,0,1]
	v_lshlrev_b32_e32 v34, 16, v2
	v_pk_fma_f32 v[0:1], v[206:207], v[30:31], v[0:1] op_sel:[0,1,0] op_sel_hi:[1,0,1]
	v_and_b32_e32 v35, 0xffff0000, v2
	v_pk_fma_f32 v[0:1], v[214:215], v[30:31], v[0:1]
	v_cvt_pk_bf16_f32 v32, v30, v31
	v_pk_fma_f32 v[30:31], v[206:207], v[0:1], v[34:35] op_sel:[0,1,0] op_sel_hi:[1,0,1]
	v_lshlrev_b32_e32 v2, 16, v3
	v_and_b32_e32 v3, 0xffff0000, v3
	v_cvt_pk_bf16_f32 v33, v0, v1
	v_pk_fma_f32 v[0:1], v[214:215], v[0:1], v[30:31]
	v_lshlrev_b32_e32 v36, 16, v4
	v_pk_fma_f32 v[2:3], v[206:207], v[0:1], v[2:3] op_sel:[0,1,0] op_sel_hi:[1,0,1]
	v_and_b32_e32 v37, 0xffff0000, v4
	v_cvt_pk_bf16_f32 v30, v0, v1
	v_pk_fma_f32 v[0:1], v[214:215], v[0:1], v[2:3]
	v_lshlrev_b32_e32 v4, 16, v5
	v_pk_fma_f32 v[2:3], v[206:207], v[0:1], v[36:37] op_sel:[0,1,0] op_sel_hi:[1,0,1]
	v_and_b32_e32 v5, 0xffff0000, v5
	v_cvt_pk_bf16_f32 v31, v0, v1
	v_pk_fma_f32 v[0:1], v[214:215], v[0:1], v[2:3]
	v_lshlrev_b32_e32 v38, 16, v6
	v_pk_fma_f32 v[2:3], v[206:207], v[0:1], v[4:5] op_sel:[0,1,0] op_sel_hi:[1,0,1]
	v_and_b32_e32 v39, 0xffff0000, v6
	ds_write2_b32 v221, v30, v31 offset0:136 offset1:204
	v_cvt_pk_bf16_f32 v30, v0, v1
	v_pk_fma_f32 v[0:1], v[214:215], v[0:1], v[2:3]
	v_lshlrev_b32_e32 v6, 16, v7
	v_pk_fma_f32 v[2:3], v[206:207], v[0:1], v[38:39] op_sel:[0,1,0] op_sel_hi:[1,0,1]
	v_and_b32_e32 v7, 0xffff0000, v7
	v_cvt_pk_bf16_f32 v4, v0, v1
	v_pk_fma_f32 v[0:1], v[214:215], v[0:1], v[2:3]
	v_lshlrev_b32_e32 v40, 16, v8
	v_pk_fma_f32 v[2:3], v[206:207], v[0:1], v[6:7] op_sel:[0,1,0] op_sel_hi:[1,0,1]
	v_and_b32_e32 v41, 0xffff0000, v8
	ds_write2_b32 v205, v30, v4 offset0:16 offset1:84
	v_cvt_pk_bf16_f32 v4, v0, v1
	v_pk_fma_f32 v[0:1], v[214:215], v[0:1], v[2:3]
	v_lshlrev_b32_e32 v8, 16, v9
	v_pk_fma_f32 v[2:3], v[206:207], v[0:1], v[40:41] op_sel:[0,1,0] op_sel_hi:[1,0,1]
	v_and_b32_e32 v9, 0xffff0000, v9
	v_cvt_pk_bf16_f32 v5, v0, v1
	v_pk_fma_f32 v[0:1], v[214:215], v[0:1], v[2:3]
	v_lshlrev_b32_e32 v42, 16, v10
	v_pk_fma_f32 v[2:3], v[206:207], v[0:1], v[8:9] op_sel:[0,1,0] op_sel_hi:[1,0,1]
	v_and_b32_e32 v43, 0xffff0000, v10
	ds_write2_b32 v205, v4, v5 offset0:152 offset1:220
	v_cvt_pk_bf16_f32 v4, v0, v1
	v_pk_fma_f32 v[0:1], v[214:215], v[0:1], v[2:3]
	v_lshlrev_b32_e32 v10, 16, v11
	v_pk_fma_f32 v[2:3], v[206:207], v[0:1], v[42:43] op_sel:[0,1,0] op_sel_hi:[1,0,1]
	v_and_b32_e32 v11, 0xffff0000, v11
	v_cvt_pk_bf16_f32 v5, v0, v1
	v_pk_fma_f32 v[0:1], v[214:215], v[0:1], v[2:3]
	v_lshlrev_b32_e32 v44, 16, v12
	v_pk_fma_f32 v[2:3], v[206:207], v[0:1], v[10:11] op_sel:[0,1,0] op_sel_hi:[1,0,1]
	v_and_b32_e32 v45, 0xffff0000, v12
	ds_write2_b32 v231, v4, v5 offset0:32 offset1:100
	v_cvt_pk_bf16_f32 v4, v0, v1
	v_pk_fma_f32 v[0:1], v[214:215], v[0:1], v[2:3]
	v_lshlrev_b32_e32 v12, 16, v13
	v_pk_fma_f32 v[2:3], v[206:207], v[0:1], v[44:45] op_sel:[0,1,0] op_sel_hi:[1,0,1]
	v_and_b32_e32 v13, 0xffff0000, v13
	v_cvt_pk_bf16_f32 v5, v0, v1
	v_pk_fma_f32 v[0:1], v[214:215], v[0:1], v[2:3]
	v_lshlrev_b32_e32 v46, 16, v14
	v_pk_fma_f32 v[2:3], v[206:207], v[0:1], v[12:13] op_sel:[0,1,0] op_sel_hi:[1,0,1]
	v_and_b32_e32 v47, 0xffff0000, v14
	ds_write2_b32 v231, v4, v5 offset0:168 offset1:236
	v_cvt_pk_bf16_f32 v4, v0, v1
	v_pk_fma_f32 v[0:1], v[214:215], v[0:1], v[2:3]
	v_lshlrev_b32_e32 v14, 16, v15
	v_pk_fma_f32 v[2:3], v[206:207], v[0:1], v[46:47] op_sel:[0,1,0] op_sel_hi:[1,0,1]
	v_and_b32_e32 v15, 0xffff0000, v15
	v_cvt_pk_bf16_f32 v5, v0, v1
	v_pk_fma_f32 v[0:1], v[214:215], v[0:1], v[2:3]
	v_lshlrev_b32_e32 v48, 16, v16
	v_pk_fma_f32 v[2:3], v[206:207], v[0:1], v[14:15] op_sel:[0,1,0] op_sel_hi:[1,0,1]
	v_and_b32_e32 v49, 0xffff0000, v16
	ds_write2_b32 v234, v4, v5 offset0:48 offset1:116
	v_cvt_pk_bf16_f32 v4, v0, v1
	v_pk_fma_f32 v[0:1], v[214:215], v[0:1], v[2:3]
	v_lshlrev_b32_e32 v16, 16, v17
	v_pk_fma_f32 v[2:3], v[206:207], v[0:1], v[48:49] op_sel:[0,1,0] op_sel_hi:[1,0,1]
	v_and_b32_e32 v17, 0xffff0000, v17
	v_cvt_pk_bf16_f32 v5, v0, v1
	v_pk_fma_f32 v[0:1], v[214:215], v[0:1], v[2:3]
	v_lshlrev_b32_e32 v50, 16, v18
	v_pk_fma_f32 v[2:3], v[206:207], v[0:1], v[16:17] op_sel:[0,1,0] op_sel_hi:[1,0,1]
	v_and_b32_e32 v51, 0xffff0000, v18
	ds_write2_b32 v234, v4, v5 offset0:184 offset1:252
	v_cvt_pk_bf16_f32 v4, v0, v1
	v_pk_fma_f32 v[0:1], v[214:215], v[0:1], v[2:3]
	v_lshlrev_b32_e32 v18, 16, v19
	v_pk_fma_f32 v[2:3], v[206:207], v[0:1], v[50:51] op_sel:[0,1,0] op_sel_hi:[1,0,1]
	v_and_b32_e32 v19, 0xffff0000, v19
	v_cvt_pk_bf16_f32 v5, v0, v1
	v_pk_fma_f32 v[0:1], v[214:215], v[0:1], v[2:3]
	ds_write2_b32 v235, v4, v5 offset0:64 offset1:132
	v_pk_fma_f32 v[2:3], v[206:207], v[0:1], v[18:19] op_sel:[0,1,0] op_sel_hi:[1,0,1]
	v_cvt_pk_bf16_f32 v4, v0, v1
	v_pk_fma_f32 v[0:1], v[214:215], v[0:1], v[2:3]
	ds_write2_b32 v221, v32, v33 offset1:68
	v_pk_fma_f32 v[2:3], v[206:207], v[0:1], v[52:53] op_sel:[0,1,0] op_sel_hi:[1,0,1]
	v_cvt_pk_bf16_f32 v5, v0, v1
	v_pk_fma_f32 v[0:1], v[214:215], v[0:1], v[2:3]
	ds_write2_b32 v236, v4, v5 offset0:72 offset1:140
	v_pk_fma_f32 v[2:3], v[212:213], v[0:1], v[54:55]
	v_cvt_pk_bf16_f32 v6, v0, v1
	v_pk_fma_f32 v[0:1], v[214:215], v[0:1], v[2:3] op_sel:[0,1,0] op_sel_hi:[1,0,1]
	v_or_b32_e32 v243, s12, v137
	v_pk_fma_f32 v[4:5], v[206:207], v[0:1], v[20:21]
	v_pk_mov_b32 v[2:3], v[0:1], v[0:1] op_sel:[1,0]
	v_pk_fma_f32 v[0:1], v[214:215], v[0:1], v[4:5] op_sel:[0,0,1] op_sel_hi:[1,1,0]
	v_cvt_pk_bf16_f32 v2, v2, v3
	v_pk_fma_f32 v[4:5], v[212:213], v[0:1], v[56:57] op_sel:[0,1,0] op_sel_hi:[1,0,1]
	ds_write2_b32 v237, v6, v2 offset0:80 offset1:148
	v_pk_mov_b32 v[2:3], v[0:1], v[0:1] op_sel:[1,0]
	v_pk_fma_f32 v[0:1], v[214:215], v[0:1], v[4:5]
	v_cvt_pk_bf16_f32 v6, v2, v3
	v_pk_fma_f32 v[4:5], v[212:213], v[0:1], v[22:23] op_sel:[0,1,0] op_sel_hi:[1,0,1]
	v_pk_mov_b32 v[2:3], v[0:1], v[0:1] op_sel:[1,0]
	v_pk_fma_f32 v[0:1], v[214:215], v[0:1], v[4:5]
	v_cvt_pk_bf16_f32 v2, v2, v3
	v_pk_fma_f32 v[4:5], v[212:213], v[0:1], v[58:59] op_sel:[0,1,0] op_sel_hi:[1,0,1]
	ds_write2_b32 v238, v6, v2 offset0:88 offset1:156
	v_pk_mov_b32 v[2:3], v[0:1], v[0:1] op_sel:[1,0]
	v_pk_fma_f32 v[0:1], v[214:215], v[0:1], v[4:5]
	v_cvt_pk_bf16_f32 v6, v2, v3
	v_pk_fma_f32 v[4:5], v[212:213], v[0:1], v[24:25] op_sel:[0,1,0] op_sel_hi:[1,0,1]
	v_pk_mov_b32 v[2:3], v[0:1], v[0:1] op_sel:[1,0]
	v_pk_fma_f32 v[0:1], v[214:215], v[0:1], v[4:5]
	v_cvt_pk_bf16_f32 v2, v2, v3
	v_pk_fma_f32 v[4:5], v[212:213], v[0:1], v[60:61] op_sel:[0,1,0] op_sel_hi:[1,0,1]
	ds_write2_b32 v239, v6, v2 offset0:96 offset1:164
	v_pk_mov_b32 v[2:3], v[0:1], v[0:1] op_sel:[1,0]
	v_pk_fma_f32 v[0:1], v[214:215], v[0:1], v[4:5]
	v_cvt_pk_bf16_f32 v6, v2, v3
	v_pk_fma_f32 v[4:5], v[212:213], v[0:1], v[26:27] op_sel:[0,1,0] op_sel_hi:[1,0,1]
	v_pk_mov_b32 v[2:3], v[0:1], v[0:1] op_sel:[1,0]
	v_pk_fma_f32 v[0:1], v[214:215], v[0:1], v[4:5]
	v_cvt_pk_bf16_f32 v2, v2, v3
	v_pk_fma_f32 v[4:5], v[212:213], v[0:1], v[62:63] op_sel:[0,1,0] op_sel_hi:[1,0,1]
	ds_write2_b32 v240, v6, v2 offset0:104 offset1:172
	v_pk_mov_b32 v[2:3], v[0:1], v[0:1] op_sel:[1,0]
	v_pk_fma_f32 v[0:1], v[214:215], v[0:1], v[4:5]
	v_cvt_pk_bf16_f32 v6, v2, v3
	v_pk_fma_f32 v[4:5], v[212:213], v[0:1], v[28:29] op_sel:[0,1,0] op_sel_hi:[1,0,1]
	v_pk_mov_b32 v[2:3], v[0:1], v[0:1] op_sel:[1,0]
	v_pk_fma_f32 v[0:1], v[214:215], v[0:1], v[4:5]
	v_cvt_pk_bf16_f32 v2, v2, v3
	v_pk_fma_f32 v[4:5], v[212:213], v[0:1], v[232:233] op_sel:[0,1,0] op_sel_hi:[1,0,1]
	ds_write2_b32 v241, v6, v2 offset0:112 offset1:180
	v_pk_fma_f32 v[216:217], v[214:215], v[0:1], v[4:5]
	v_pk_mov_b32 v[2:3], v[0:1], v[0:1] op_sel:[1,0]
	v_pk_mov_b32 v[0:1], v[216:217], v[216:217] op_sel:[1,0]
	v_cvt_pk_bf16_f32 v2, v2, v3
	v_cvt_pk_bf16_f32 v0, v0, v1
	ds_write2_b32 v242, v2, v0 offset0:120 offset1:188
	s_waitcnt lgkmcnt(0)
	ds_read_b128 v[0:3], v222
	ds_read_b128 v[4:7], v222 offset:64
	s_waitcnt lgkmcnt(1)
	v_mfma_f32_16x16x32_bf16 v[0:3], v[80:83], v[0:3], 0
	v_mad_u32_u24 v18, v243, s17, v203
	ds_read_b64 v[12:13], v18
	ds_read_b128 v[8:11], v222 offset:128
	v_mov_b64_e32 v[218:219], s[20:21]
	s_waitcnt lgkmcnt(2)
	v_mfma_f32_16x16x32_bf16 v[0:3], v[84:87], v[4:7], v[0:3]
	ds_read_b128 v[4:7], v222 offset:192
	ds_read_b64 v[14:15], v18 offset:16640
	s_waitcnt lgkmcnt(3)
	v_lshlrev_b32_e32 v16, 16, v12
	v_and_b32_e32 v17, 0xffff0000, v12
	s_waitcnt lgkmcnt(2)
	v_mfma_f32_16x16x32_bf16 v[0:3], v[88:91], v[8:11], v[0:3]
	v_lshlrev_b32_e32 v8, 16, v13
	v_and_b32_e32 v9, 0xffff0000, v13
	s_mov_b32 s12, 32
	s_waitcnt lgkmcnt(1)
	v_mfma_f32_16x16x32_bf16 v[0:3], v[92:95], v[4:7], v[0:3]
	s_nop 7
	v_pk_fma_f32 v[0:1], v[96:97], v[16:17], v[0:1]
	v_pk_fma_f32 v[2:3], v[98:99], v[8:9], v[2:3]
	v_and_b32_e32 v5, 0x7fffffff, v1
	v_and_b32_e32 v4, 0x7fffffff, v0
	v_and_b32_e32 v9, 0x7fffffff, v3
	v_and_b32_e32 v8, 0x7fffffff, v2
	v_pk_fma_f32 v[4:5], v[4:5], s[16:17], 1.0 op_sel_hi:[1,0,0]
	v_pk_fma_f32 v[8:9], v[8:9], s[16:17], 1.0 op_sel_hi:[1,0,0]
	v_rcp_f32_e32 v4, v4
	v_rcp_f32_e32 v5, v5
	v_rcp_f32_e32 v8, v8
	v_rcp_f32_e32 v9, v9
	v_pk_mul_f32 v[6:7], v[0:1], v[0:1]
	v_pk_mul_f32 v[10:11], v[2:3], v[2:3]
	v_pk_mul_f32 v[6:7], v[6:7], s[28:29] op_sel_hi:[1,0]
	v_pk_mul_f32 v[10:11], v[10:11], s[28:29] op_sel_hi:[1,0]
	v_pk_fma_f32 v[12:13], v[4:5], s[18:19], v[218:219] op_sel_hi:[1,0,0]
	v_pk_fma_f32 v[16:17], v[8:9], s[18:19], v[218:219] op_sel_hi:[1,0,0]
	v_exp_f32_e32 v6, v6
	v_exp_f32_e32 v7, v7
	v_exp_f32_e32 v10, v10
	v_exp_f32_e32 v11, v11
	v_pk_fma_f32 v[12:13], v[4:5], v[12:13], s[22:23] op_sel_hi:[1,1,0]
	v_pk_fma_f32 v[16:17], v[8:9], v[16:17], s[22:23] op_sel_hi:[1,1,0]
	v_pk_fma_f32 v[12:13], v[4:5], v[12:13], s[24:25] op_sel_hi:[1,1,0]
	v_pk_fma_f32 v[16:17], v[8:9], v[16:17], s[24:25] op_sel_hi:[1,1,0]
	v_pk_fma_f32 v[12:13], v[4:5], v[12:13], s[26:27] op_sel_hi:[1,1,0]
	v_pk_fma_f32 v[16:17], v[8:9], v[16:17], s[26:27] op_sel_hi:[1,1,0]
	v_pk_mul_f32 v[4:5], v[4:5], v[12:13]
	v_pk_mul_f32 v[8:9], v[8:9], v[16:17]
	v_pk_mul_f32 v[4:5], v[6:7], v[4:5]
	v_pk_mul_f32 v[6:7], v[10:11], v[8:9]
	v_pk_mul_f32 v[8:9], v[0:1], v[4:5]
	v_pk_fma_f32 v[4:5], v[0:1], v[4:5], v[0:1] neg_lo:[1,0,0] neg_hi:[1,0,0]
	v_cmp_gt_f32_e32 vcc, 0, v0
	v_pk_mul_f32 v[10:11], v[2:3], v[6:7]
	v_pk_fma_f32 v[6:7], v[2:3], v[6:7], v[2:3] neg_lo:[1,0,0] neg_hi:[1,0,0]
	v_cmp_gt_f32_e64 s[4:5], 0, v2
	v_cmp_gt_f32_e64 s[6:7], 0, v3
	v_cmp_gt_f32_e64 s[8:9], 0, v1
	v_cndmask_b32_e32 v1, v4, v8, vcc
	v_cndmask_b32_e64 v2, v7, v11, s[6:7]
	v_cndmask_b32_e64 v0, v5, v9, s[8:9]
	v_cndmask_b32_e64 v3, v6, v10, s[4:5]
	v_cvt_pk_bf16_f32 v0, v1, v0
	v_cvt_pk_bf16_f32 v1, v3, v2
	ds_write_b64 v18, v[0:1]
	ds_read_b128 v[0:3], v222 offset:4352
	ds_read_b128 v[4:7], v222 offset:4416
	s_waitcnt lgkmcnt(1)
	v_mfma_f32_16x16x32_bf16 v[0:3], v[80:83], v[0:3], 0
	v_lshlrev_b32_e32 v12, 16, v14
	v_and_b32_e32 v13, 0xffff0000, v14
	s_waitcnt lgkmcnt(0)
	v_mfma_f32_16x16x32_bf16 v[0:3], v[84:87], v[4:7], v[0:3]
	ds_read_b128 v[4:7], v222 offset:4480
	ds_read_b128 v[8:11], v222 offset:4544
	s_waitcnt lgkmcnt(1)
	v_mfma_f32_16x16x32_bf16 v[0:3], v[88:91], v[4:7], v[0:3]
	v_lshlrev_b32_e32 v4, 16, v15
	v_and_b32_e32 v5, 0xffff0000, v15
	s_waitcnt lgkmcnt(0)
	v_mfma_f32_16x16x32_bf16 v[0:3], v[92:95], v[8:11], v[0:3]
	s_nop 7
	v_pk_fma_f32 v[0:1], v[96:97], v[12:13], v[0:1]
	v_pk_fma_f32 v[2:3], v[98:99], v[4:5], v[2:3]
	v_and_b32_e32 v5, 0x7fffffff, v1
	v_and_b32_e32 v4, 0x7fffffff, v0
	v_and_b32_e32 v9, 0x7fffffff, v3
	v_and_b32_e32 v8, 0x7fffffff, v2
	v_pk_fma_f32 v[4:5], v[4:5], s[16:17], 1.0 op_sel_hi:[1,0,0]
	v_pk_fma_f32 v[8:9], v[8:9], s[16:17], 1.0 op_sel_hi:[1,0,0]
	v_rcp_f32_e32 v4, v4
	v_rcp_f32_e32 v5, v5
	v_rcp_f32_e32 v8, v8
	v_rcp_f32_e32 v9, v9
	v_pk_mul_f32 v[6:7], v[0:1], v[0:1]
	v_pk_mul_f32 v[10:11], v[2:3], v[2:3]
	v_pk_mul_f32 v[6:7], v[6:7], s[28:29] op_sel_hi:[1,0]
	v_pk_mul_f32 v[10:11], v[10:11], s[28:29] op_sel_hi:[1,0]
	v_pk_fma_f32 v[12:13], v[4:5], s[18:19], v[218:219] op_sel_hi:[1,0,0]
	v_pk_fma_f32 v[14:15], v[8:9], s[18:19], v[218:219] op_sel_hi:[1,0,0]
	v_exp_f32_e32 v6, v6
	v_exp_f32_e32 v7, v7
	v_exp_f32_e32 v10, v10
	v_exp_f32_e32 v11, v11
	v_pk_fma_f32 v[12:13], v[4:5], v[12:13], s[22:23] op_sel_hi:[1,1,0]
	v_pk_fma_f32 v[14:15], v[8:9], v[14:15], s[22:23] op_sel_hi:[1,1,0]
	v_pk_fma_f32 v[12:13], v[4:5], v[12:13], s[24:25] op_sel_hi:[1,1,0]
	v_pk_fma_f32 v[14:15], v[8:9], v[14:15], s[24:25] op_sel_hi:[1,1,0]
	v_pk_fma_f32 v[12:13], v[4:5], v[12:13], s[26:27] op_sel_hi:[1,1,0]
	v_pk_fma_f32 v[14:15], v[8:9], v[14:15], s[26:27] op_sel_hi:[1,1,0]
	v_pk_mul_f32 v[4:5], v[4:5], v[12:13]
	v_pk_mul_f32 v[8:9], v[8:9], v[14:15]
	v_pk_mul_f32 v[4:5], v[6:7], v[4:5]
	v_pk_mul_f32 v[6:7], v[10:11], v[8:9]
	v_pk_mul_f32 v[8:9], v[0:1], v[4:5]
	v_pk_fma_f32 v[4:5], v[0:1], v[4:5], v[0:1] neg_lo:[1,0,0] neg_hi:[1,0,0]
	v_cmp_gt_f32_e32 vcc, 0, v0
	v_pk_mul_f32 v[10:11], v[2:3], v[6:7]
	v_pk_fma_f32 v[6:7], v[2:3], v[6:7], v[2:3] neg_lo:[1,0,0] neg_hi:[1,0,0]
	v_cmp_gt_f32_e64 s[4:5], 0, v2
	v_cmp_gt_f32_e64 s[6:7], 0, v3
	v_cmp_gt_f32_e64 s[8:9], 0, v1
	v_cndmask_b32_e32 v1, v4, v8, vcc
	v_cndmask_b32_e64 v2, v7, v11, s[6:7]
	v_cndmask_b32_e64 v0, v5, v9, s[8:9]
	v_cndmask_b32_e64 v3, v6, v10, s[4:5]
	v_cvt_pk_bf16_f32 v0, v1, v0
	v_cvt_pk_bf16_f32 v1, v3, v2
	ds_write_b64 v18, v[0:1] offset:16640
	s_waitcnt lgkmcnt(0)
	s_andn2_b64 vcc, exec, s[48:49]
	s_mov_b64 s[48:49], 0
	s_cbranch_vccz .LBB0_456
	s_add_i32 s39, s39, 1
	s_waitcnt vmcnt(3)
	v_mov_b64_e32 v[80:81], v[116:117]
	s_waitcnt vmcnt(2)
	v_mov_b64_e32 v[84:85], v[120:121]
	s_waitcnt vmcnt(1)
	v_mov_b64_e32 v[88:89], v[128:129]
	s_waitcnt vmcnt(0)
	v_mov_b64_e32 v[92:93], v[132:133]
	v_mov_b64_e32 v[64:65], v[100:101]
	v_mov_b64_e32 v[68:69], v[104:105]
	v_mov_b64_e32 v[72:73], v[108:109]
	v_mov_b64_e32 v[76:77], v[112:113]
	v_mov_b64_e32 v[96:97], v[124:125]
	s_cmp_eq_u32 s39, 4
	v_mov_b64_e32 v[82:83], v[118:119]
	v_mov_b64_e32 v[86:87], v[122:123]
	v_mov_b64_e32 v[90:91], v[130:131]
	v_mov_b64_e32 v[94:95], v[134:135]
	v_mov_b64_e32 v[66:67], v[102:103]
	v_mov_b64_e32 v[70:71], v[106:107]
	v_mov_b64_e32 v[74:75], v[110:111]
	v_mov_b64_e32 v[78:79], v[114:115]
	v_mov_b64_e32 v[206:207], v[210:211]
	v_mov_b64_e32 v[0:1], v[208:209]
	v_mov_b64_e32 v[98:99], v[126:127]
	s_cbranch_scc0 .LBB0_453
	s_waitcnt lgkmcnt(0)
	global_load_dwordx4 v[64:67], v[168:169], off
	global_load_dwordx4 v[68:71], v[168:169], off offset:32
	global_load_dwordx4 v[72:75], v[170:171], off
	global_load_dwordx4 v[76:79], v[172:173], off
	global_load_dwordx4 v[80:83], v[168:169], off offset:64
	global_load_dwordx4 v[84:87], v[168:169], off offset:96
	global_load_dwordx4 v[88:91], v[174:175], off
	global_load_dwordx4 v[92:95], v[176:177], off
	s_barrier
	v_mov_b32_e32 v0, 0
	s_mov_b32 s6, 0
	v_mov_b32_e32 v130, v195
	v_mov_b32_e32 v131, v191
	v_mov_b64_e32 v[128:129], v[200:201]
	v_mov_b32_e32 v1, v0
	v_mov_b32_e32 v2, v0
	v_mov_b32_e32 v3, v0
	v_mov_b32_e32 v4, v0
	v_mov_b32_e32 v5, v0
	v_mov_b32_e32 v6, v0
	v_mov_b32_e32 v7, v0
	v_mov_b32_e32 v8, v0
	v_mov_b32_e32 v9, v0
	v_mov_b32_e32 v10, v0
	v_mov_b32_e32 v11, v0
	v_mov_b32_e32 v12, v0
	v_mov_b32_e32 v13, v0
	v_mov_b32_e32 v14, v0
	v_mov_b32_e32 v15, v0
	v_mov_b32_e32 v32, v0
	v_mov_b32_e32 v33, v0
	v_mov_b32_e32 v34, v0
	v_mov_b32_e32 v35, v0
	v_mov_b32_e32 v36, v0
	v_mov_b32_e32 v37, v0
	v_mov_b32_e32 v38, v0
	v_mov_b32_e32 v39, v0
	v_mov_b32_e32 v40, v0
	v_mov_b32_e32 v41, v0
	v_mov_b32_e32 v42, v0
	v_mov_b32_e32 v43, v0
	v_mov_b32_e32 v44, v0
	v_mov_b32_e32 v45, v0
	v_mov_b32_e32 v46, v0
	v_mov_b32_e32 v47, v0
	v_mov_b32_e32 v16, v0
	v_mov_b32_e32 v17, v0
	v_mov_b32_e32 v18, v0
	v_mov_b32_e32 v19, v0
	v_mov_b32_e32 v20, v0
	v_mov_b32_e32 v21, v0
	v_mov_b32_e32 v22, v0
	v_mov_b32_e32 v23, v0
	v_mov_b32_e32 v24, v0
	v_mov_b32_e32 v25, v0
	v_mov_b32_e32 v26, v0
	v_mov_b32_e32 v27, v0
	v_mov_b32_e32 v28, v0
	v_mov_b32_e32 v29, v0
	v_mov_b32_e32 v30, v0
	v_mov_b32_e32 v31, v0
	v_mov_b32_e32 v48, v0
	v_mov_b32_e32 v49, v0
	v_mov_b32_e32 v50, v0
	v_mov_b32_e32 v51, v0
	v_mov_b32_e32 v52, v0
	v_mov_b32_e32 v53, v0
	v_mov_b32_e32 v54, v0
	v_mov_b32_e32 v55, v0
	v_mov_b32_e32 v56, v0
	v_mov_b32_e32 v57, v0
	v_mov_b32_e32 v58, v0
	v_mov_b32_e32 v59, v0
	v_mov_b32_e32 v60, v0
	v_mov_b32_e32 v61, v0
	v_mov_b32_e32 v62, v0
	v_mov_b32_e32 v63, v0
	s_branch .LBB0_460

.Lglu_mma1_steady:
	v_add_u32_e32 v134, 0x11080, v132
	ds_read_b128 v[206:209], v134
	v_add_u32_e32 v134, 0x11080, v133
	ds_read_b128 v[210:213], v134
	s_add_i32 s6, s6, 2
	s_waitcnt vmcnt(15) lgkmcnt(1)
	v_mfma_f32_32x32x16_bf16 v[48:63], v[124:127], v[206:209], v[48:63]
	v_lshl_add_u64 v[128:129], v[128:129], 0, s[30:31]
	v_add_u32_e32 v131, 0x100, v131
	v_add_u32_e32 v130, 0x100, v130
	s_and_b64 vcc, exec, s[4:5]
	s_waitcnt lgkmcnt(0)
	v_mfma_f32_32x32x16_bf16 v[16:31], v[124:127], v[210:213], v[16:31]
	v_add_u32_e32 v124, 0x110a0, v133
	ds_read_b128 v[124:127], v124
	s_waitcnt vmcnt(13)
	v_mfma_f32_32x32x16_bf16 v[32:47], v[120:123], v[206:209], v[32:47]
	v_mfma_f32_32x32x16_bf16 v[0:15], v[120:123], v[210:213], v[0:15]
	v_add_u32_e32 v120, 0x110a0, v132
	ds_read_b128 v[120:123], v120
	s_waitcnt lgkmcnt(0)
	v_mfma_f32_32x32x16_bf16 v[48:63], v[116:119], v[120:123], v[48:63]
	v_mfma_f32_32x32x16_bf16 v[16:31], v[116:119], v[124:127], v[16:31]
	v_add_u32_e32 v116, 0x110c0, v133
	ds_read_b128 v[116:119], v116
	s_waitcnt vmcnt(12)
	v_mfma_f32_32x32x16_bf16 v[32:47], v[112:115], v[120:123], v[32:47]
	v_mfma_f32_32x32x16_bf16 v[0:15], v[112:115], v[124:127], v[0:15]
	v_add_u32_e32 v112, 0x110c0, v132
	ds_read_b128 v[112:115], v112
	s_waitcnt vmcnt(11) lgkmcnt(0)
	v_mfma_f32_32x32x16_bf16 v[48:63], v[108:111], v[112:115], v[48:63]
	v_mfma_f32_32x32x16_bf16 v[16:31], v[108:111], v[116:119], v[16:31]
	v_add_u32_e32 v108, 0x110e0, v133
	ds_read_b128 v[108:111], v108
	s_waitcnt vmcnt(9)
	v_mfma_f32_32x32x16_bf16 v[32:47], v[104:107], v[112:115], v[32:47]
	v_mfma_f32_32x32x16_bf16 v[0:15], v[104:107], v[116:119], v[0:15]
	v_add_u32_e32 v104, 0x110e0, v132
	ds_read_b128 v[104:107], v104
	s_waitcnt lgkmcnt(0)
	v_mfma_f32_32x32x16_bf16 v[48:63], v[100:103], v[104:107], v[48:63]
	v_mfma_f32_32x32x16_bf16 v[16:31], v[100:103], v[108:111], v[16:31]
	s_waitcnt vmcnt(8)
	v_mfma_f32_32x32x16_bf16 v[32:47], v[96:99], v[104:107], v[32:47]
	v_mfma_f32_32x32x16_bf16 v[0:15], v[96:99], v[108:111], v[0:15]
	s_cbranch_vccnz .LBB0_462
	s_branch .LBB0_460
